# EpiRelu2: removed 128 redundant canonicalizing v_max per wave per unit (identity on MFMA results), hazard pads kept
# speedup vs baseline: 1.0086x; 1.0037x over previous
; __device__ __forceinline__ unsigned cvt_pk_bf16(float lo, float hi) { unsigned r; asm volatile("v_cvt_pk_bf16_f32 %0, %1, %2" : "=v"(r) : "v"(lo), "v"(hi)); return r; }
;     __device__ __forceinline__ void operator()(const f32x4 (&acc)[2][2][4][2], const Unit& u, int wr, int wc, int fr, int fq) const {
;         const int row0 = u.pm * BM + wr * 64 + fr, col0 = u.pn * BM + wc * 32 + 8 * fq;
; #pragma unroll
;         for (int ai = 0; ai < 2; ++ai)
; #pragma unroll
;             for (int m = 0; m < 4; ++m) {
;                 bf16_t* rowp = O + (size_t)(row0 + ai * HALF + m * 16) * ldc + col0;
; #pragma unroll
;                 for (int bj = 0; bj < 2; ++bj) {
;                     f32x4 v0 = acc[ai][bj][m][0], v1 = acc[ai][bj][m][1];
;                     v0 = __builtin_elementwise_max(v0, (f32x4){0.f, 0.f, 0.f, 0.f}); v1 = __builtin_elementwise_max(v1, (f32x4){0.f, 0.f, 0.f, 0.f});
;                     v0 = v0 * v0; v1 = v1 * v1;
;                     u32x4 w; w.x = cvt_pk_bf16(v0[0], v0[1]); w.y = cvt_pk_bf16(v0[2], v0[3]); w.z = cvt_pk_bf16(v1[0], v1[1]); w.w = cvt_pk_bf16(v1[2], v1[3]);
;                     __builtin_nontemporal_store(w, (u32x4*)(rowp + bj * HALF));
;                 }
;             }
.LBB0_1249:
	v_lshl_add_u32 v140, s72, 8, v144
	v_lshl_or_b32 v138, s90, 8, v146
	v_ashrrev_i32_e32 v141, 31, v140
	v_ashrrev_i32_e32 v139, 31, v138
	v_lshlrev_b64 v[142:143], 13, v[140:141]
	v_lshl_add_u64 v[148:149], s[4:5], 0, v[142:143]
	v_lshlrev_b64 v[142:143], 1, v[138:139]
	v_max_f32_e32 v125, 0, v125
	v_max_f32_e32 v124, 0, v124
	v_max_f32_e32 v127, 0, v127
	v_max_f32_e32 v126, 0, v126
	v_max_f32_e32 v121, 0, v121
	v_max_f32_e32 v120, 0, v120
	v_max_f32_e32 v123, 0, v123
	v_max_f32_e32 v122, 0, v122
	v_lshl_add_u64 v[138:139], v[148:149], 0, v[142:143]
	v_pk_mul_f32 v[126:127], v[126:127], v[126:127]
	v_pk_mul_f32 v[124:125], v[124:125], v[124:125]
	v_pk_mul_f32 v[148:149], v[122:123], v[122:123]
	v_pk_mul_f32 v[122:123], v[120:121], v[120:121]
	v_cvt_pk_bf16_f32 v120, v124, v125
	v_cvt_pk_bf16_f32 v121, v126, v127
	v_max_f32_e32 v117, 0, v117
	v_max_f32_e32 v116, 0, v116
	v_max_f32_e32 v113, 0, v113
	v_max_f32_e32 v112, 0, v112
	v_max_f32_e32 v115, 0, v115
	v_max_f32_e32 v114, 0, v114
	v_cvt_pk_bf16_f32 v122, v122, v123
	v_cvt_pk_bf16_f32 v123, v148, v149
	global_store_dwordx4 v[138:139], v[120:123], off nt
	v_max_f32_e32 v119, 0, v119
	v_max_f32_e32 v118, 0, v118
	v_pk_mul_f32 v[116:117], v[116:117], v[116:117]
	v_pk_mul_f32 v[120:121], v[114:115], v[114:115]
	v_pk_mul_f32 v[114:115], v[112:113], v[112:113]
	v_cvt_pk_bf16_f32 v112, v116, v117
	v_pk_mul_f32 v[118:119], v[118:119], v[118:119]
	v_cvt_pk_bf16_f32 v113, v118, v119
	v_cvt_pk_bf16_f32 v114, v114, v115
	v_cvt_pk_bf16_f32 v115, v120, v121
	global_store_dwordx4 v[138:139], v[112:115], off offset:256 nt
	s_nop 1
	v_or_b32_e32 v112, 16, v140
	v_ashrrev_i32_e32 v113, 31, v112
	v_lshlrev_b64 v[112:113], 13, v[112:113]
	v_lshl_add_u64 v[112:113], s[4:5], 0, v[112:113]
	v_max_f32_e32 v109, 0, v109
	v_max_f32_e32 v108, 0, v108
	v_max_f32_e32 v111, 0, v111
	v_max_f32_e32 v110, 0, v110
	v_max_f32_e32 v105, 0, v105
	v_max_f32_e32 v104, 0, v104
	v_max_f32_e32 v107, 0, v107
	v_max_f32_e32 v106, 0, v106
	v_lshl_add_u64 v[112:113], v[112:113], 0, v[142:143]
	v_pk_mul_f32 v[110:111], v[110:111], v[110:111]
	v_pk_mul_f32 v[108:109], v[108:109], v[108:109]
	v_pk_mul_f32 v[114:115], v[106:107], v[106:107]
	v_pk_mul_f32 v[106:107], v[104:105], v[104:105]
	v_cvt_pk_bf16_f32 v104, v108, v109
	v_cvt_pk_bf16_f32 v105, v110, v111
	v_max_f32_e32 v101, 0, v101
	v_max_f32_e32 v100, 0, v100
	v_max_f32_e32 v97, 0, v97
	v_max_f32_e32 v96, 0, v96
	v_max_f32_e32 v99, 0, v99
	v_max_f32_e32 v98, 0, v98
	v_cvt_pk_bf16_f32 v106, v106, v107
	v_cvt_pk_bf16_f32 v107, v114, v115
	global_store_dwordx4 v[112:113], v[104:107], off nt
	v_max_f32_e32 v103, 0, v103
	v_max_f32_e32 v102, 0, v102
	v_pk_mul_f32 v[100:101], v[100:101], v[100:101]
	v_pk_mul_f32 v[104:105], v[98:99], v[98:99]
	v_pk_mul_f32 v[98:99], v[96:97], v[96:97]
	v_cvt_pk_bf16_f32 v96, v100, v101
	v_pk_mul_f32 v[102:103], v[102:103], v[102:103]
	v_cvt_pk_bf16_f32 v97, v102, v103
	v_cvt_pk_bf16_f32 v98, v98, v99
	v_cvt_pk_bf16_f32 v99, v104, v105
	global_store_dwordx4 v[112:113], v[96:99], off offset:256 nt
	s_nop 1
	v_or_b32_e32 v96, 32, v140
	v_ashrrev_i32_e32 v97, 31, v96
	v_lshlrev_b64 v[96:97], 13, v[96:97]
	v_lshl_add_u64 v[96:97], s[4:5], 0, v[96:97]
	v_max_f32_e32 v93, 0, v93
	v_max_f32_e32 v92, 0, v92
	v_max_f32_e32 v95, 0, v95
	v_max_f32_e32 v94, 0, v94
	v_max_f32_e32 v89, 0, v89
	v_max_f32_e32 v88, 0, v88
	v_max_f32_e32 v91, 0, v91
	v_max_f32_e32 v90, 0, v90
	v_lshl_add_u64 v[96:97], v[96:97], 0, v[142:143]
	v_pk_mul_f32 v[94:95], v[94:95], v[94:95]
	v_pk_mul_f32 v[92:93], v[92:93], v[92:93]
	v_pk_mul_f32 v[98:99], v[90:91], v[90:91]
	v_pk_mul_f32 v[90:91], v[88:89], v[88:89]
	v_cvt_pk_bf16_f32 v88, v92, v93
	v_cvt_pk_bf16_f32 v89, v94, v95
	v_max_f32_e32 v85, 0, v85
	v_max_f32_e32 v84, 0, v84
	v_max_f32_e32 v81, 0, v81
	v_max_f32_e32 v80, 0, v80
	v_max_f32_e32 v83, 0, v83
	v_max_f32_e32 v82, 0, v82
	v_cvt_pk_bf16_f32 v90, v90, v91
	v_cvt_pk_bf16_f32 v91, v98, v99
	global_store_dwordx4 v[96:97], v[88:91], off nt
	v_max_f32_e32 v87, 0, v87
	v_max_f32_e32 v86, 0, v86
	v_pk_mul_f32 v[84:85], v[84:85], v[84:85]
	v_pk_mul_f32 v[88:89], v[82:83], v[82:83]
	v_pk_mul_f32 v[82:83], v[80:81], v[80:81]
	v_cvt_pk_bf16_f32 v80, v84, v85
	v_pk_mul_f32 v[86:87], v[86:87], v[86:87]
	v_cvt_pk_bf16_f32 v81, v86, v87
	v_cvt_pk_bf16_f32 v82, v82, v83
	v_cvt_pk_bf16_f32 v83, v88, v89
	global_store_dwordx4 v[96:97], v[80:83], off offset:256 nt
	s_nop 1
	v_or_b32_e32 v80, 48, v140
	v_ashrrev_i32_e32 v81, 31, v80
	v_lshlrev_b64 v[80:81], 13, v[80:81]
	v_lshl_add_u64 v[80:81], s[4:5], 0, v[80:81]
	v_max_f32_e32 v77, 0, v77
	v_max_f32_e32 v76, 0, v76
	v_max_f32_e32 v79, 0, v79
	v_max_f32_e32 v78, 0, v78
	v_max_f32_e32 v73, 0, v73
	v_max_f32_e32 v72, 0, v72
	v_max_f32_e32 v75, 0, v75
	v_max_f32_e32 v74, 0, v74
	v_lshl_add_u64 v[80:81], v[80:81], 0, v[142:143]
	v_pk_mul_f32 v[78:79], v[78:79], v[78:79]
	v_pk_mul_f32 v[76:77], v[76:77], v[76:77]
	v_pk_mul_f32 v[82:83], v[74:75], v[74:75]
	v_pk_mul_f32 v[74:75], v[72:73], v[72:73]
	v_cvt_pk_bf16_f32 v72, v76, v77
	v_cvt_pk_bf16_f32 v73, v78, v79
	v_max_f32_e32 v65, 0, v65
	v_max_f32_e32 v64, 0, v64
	v_max_f32_e32 v67, 0, v67
	v_max_f32_e32 v66, 0, v66
	v_cvt_pk_bf16_f32 v74, v74, v75
	v_cvt_pk_bf16_f32 v75, v82, v83
	global_store_dwordx4 v[80:81], v[72:75], off nt
	v_max_f32_e32 v69, 0, v69
	v_max_f32_e32 v68, 0, v68
	v_max_f32_e32 v71, 0, v71
	v_max_f32_e32 v70, 0, v70
	v_pk_mul_f32 v[72:73], v[66:67], v[66:67]
	v_pk_mul_f32 v[66:67], v[64:65], v[64:65]
	v_max_f32_e32 v61, 0, v61
	v_max_f32_e32 v60, 0, v60
	v_pk_mul_f32 v[70:71], v[70:71], v[70:71]
	v_pk_mul_f32 v[68:69], v[68:69], v[68:69]
; __device__ __forceinline__ unsigned cvt_pk_bf16(float lo, float hi) { unsigned r; asm volatile("v_cvt_pk_bf16_f32 %0, %1, %2" : "=v"(r) : "v"(lo), "v"(hi)); return r; }
;     __device__ __forceinline__ void operator()(const f32x4 (&acc)[2][2][4][2], const Unit& u, int wr, int wc, int fr, int fq) const {
;         const int row0 = u.pm * BM + wr * 64 + fr, col0 = u.pn * BM + wc * 32 + 8 * fq;
; #pragma unroll
;         for (int ai = 0; ai < 2; ++ai)
; #pragma unroll
;             for (int m = 0; m < 4; ++m) {
;                 bf16_t* rowp = O + (size_t)(row0 + ai * HALF + m * 16) * ldc + col0;
; #pragma unroll
;                 for (int bj = 0; bj < 2; ++bj) {
;                     f32x4 v0 = acc[ai][bj][m][0], v1 = acc[ai][bj][m][1];
;                     v0 = __builtin_elementwise_max(v0, (f32x4){0.f, 0.f, 0.f, 0.f}); v1 = __builtin_elementwise_max(v1, (f32x4){0.f, 0.f, 0.f, 0.f});
;                     v0 = v0 * v0; v1 = v1 * v1;
;                     u32x4 w; w.x = cvt_pk_bf16(v0[0], v0[1]); w.y = cvt_pk_bf16(v0[2], v0[3]); w.z = cvt_pk_bf16(v1[0], v1[1]); w.w = cvt_pk_bf16(v1[2], v1[3]);
;                     __builtin_nontemporal_store(w, (u32x4*)(rowp + bj * HALF));
;                 }
;             }
	v_cvt_pk_bf16_f32 v64, v68, v69
	v_cvt_pk_bf16_f32 v65, v70, v71
	v_cvt_pk_bf16_f32 v66, v66, v67
	v_cvt_pk_bf16_f32 v67, v72, v73
	v_max_f32_e32 v57, 0, v57
	v_max_f32_e32 v56, 0, v56
	v_max_f32_e32 v59, 0, v59
	v_max_f32_e32 v58, 0, v58
	v_pk_mul_f32 v[60:61], v[60:61], v[60:61]
	s_mov_b32 s16, 0x100000
	global_store_dwordx4 v[80:81], v[64:67], off offset:256 nt
	v_max_f32_e32 v63, 0, v63
	v_max_f32_e32 v62, 0, v62
	v_pk_mul_f32 v[66:67], v[58:59], v[58:59]
	v_pk_mul_f32 v[58:59], v[56:57], v[56:57]
	v_cvt_pk_bf16_f32 v56, v60, v61
	v_add_co_u32_e32 v60, vcc, s16, v138
	v_pk_mul_f32 v[62:63], v[62:63], v[62:63]
	v_addc_co_u32_e32 v61, vcc, 0, v139, vcc
	v_cvt_pk_bf16_f32 v57, v62, v63
	v_max_f32_e32 v53, 0, v53
	v_max_f32_e32 v52, 0, v52
	v_max_f32_e32 v55, 0, v55
	v_max_f32_e32 v54, 0, v54
	v_max_f32_e32 v49, 0, v49
	v_max_f32_e32 v48, 0, v48
	v_max_f32_e32 v51, 0, v51
	v_max_f32_e32 v50, 0, v50
	v_lshl_add_u64 v[64:65], v[138:139], 0, s[26:27]
	v_cvt_pk_bf16_f32 v58, v58, v59
	v_cvt_pk_bf16_f32 v59, v66, v67
	global_store_dwordx4 v[60:61], v[56:59], off nt
	v_pk_mul_f32 v[54:55], v[54:55], v[54:55]
	v_pk_mul_f32 v[52:53], v[52:53], v[52:53]
	v_pk_mul_f32 v[56:57], v[50:51], v[50:51]
	v_pk_mul_f32 v[50:51], v[48:49], v[48:49]
	v_cvt_pk_bf16_f32 v48, v52, v53
	v_cvt_pk_bf16_f32 v49, v54, v55
	s_mov_b64 s[16:17], 0x120000
	v_max_f32_e32 v45, 0, v45
	v_max_f32_e32 v44, 0, v44
	v_cvt_pk_bf16_f32 v50, v50, v51
	v_cvt_pk_bf16_f32 v51, v56, v57
	global_store_dwordx4 v[64:65], v[48:51], off offset:256 nt
	s_nop 1
	v_lshl_add_u64 v[48:49], v[138:139], 0, s[16:17]
	v_max_f32_e32 v41, 0, v41
	v_max_f32_e32 v40, 0, v40
	v_max_f32_e32 v43, 0, v43
	v_max_f32_e32 v42, 0, v42
	v_pk_mul_f32 v[44:45], v[44:45], v[44:45]
	s_mov_b32 s16, 0x120000
	v_max_f32_e32 v47, 0, v47
	v_max_f32_e32 v46, 0, v46
	v_pk_mul_f32 v[50:51], v[42:43], v[42:43]
	v_pk_mul_f32 v[42:43], v[40:41], v[40:41]
	v_cvt_pk_bf16_f32 v40, v44, v45
	v_add_co_u32_e32 v44, vcc, s16, v138
	v_pk_mul_f32 v[46:47], v[46:47], v[46:47]
	v_addc_co_u32_e32 v45, vcc, 0, v139, vcc
	v_cvt_pk_bf16_f32 v41, v46, v47
	v_max_f32_e32 v37, 0, v37
	v_max_f32_e32 v36, 0, v36
	v_max_f32_e32 v39, 0, v39
	v_max_f32_e32 v38, 0, v38
	v_max_f32_e32 v33, 0, v33
	v_max_f32_e32 v32, 0, v32
	v_max_f32_e32 v35, 0, v35
	v_max_f32_e32 v34, 0, v34
	v_cvt_pk_bf16_f32 v42, v42, v43
	v_cvt_pk_bf16_f32 v43, v50, v51
	global_store_dwordx4 v[44:45], v[40:43], off nt
	v_pk_mul_f32 v[38:39], v[38:39], v[38:39]
	v_pk_mul_f32 v[36:37], v[36:37], v[36:37]
	v_pk_mul_f32 v[40:41], v[34:35], v[34:35]
	v_pk_mul_f32 v[34:35], v[32:33], v[32:33]
	v_cvt_pk_bf16_f32 v32, v36, v37
	v_cvt_pk_bf16_f32 v33, v38, v39
	s_mov_b64 s[16:17], 0x140000
	v_max_f32_e32 v29, 0, v29
	v_max_f32_e32 v28, 0, v28
	v_cvt_pk_bf16_f32 v34, v34, v35
	v_cvt_pk_bf16_f32 v35, v40, v41
	global_store_dwordx4 v[48:49], v[32:35], off offset:256 nt
	s_nop 1
	v_lshl_add_u64 v[32:33], v[138:139], 0, s[16:17]
	v_max_f32_e32 v25, 0, v25
	v_max_f32_e32 v24, 0, v24
	v_max_f32_e32 v27, 0, v27
	v_max_f32_e32 v26, 0, v26
	v_pk_mul_f32 v[28:29], v[28:29], v[28:29]
	s_mov_b32 s16, 0x140000
	v_max_f32_e32 v31, 0, v31
	v_max_f32_e32 v30, 0, v30
	v_pk_mul_f32 v[34:35], v[26:27], v[26:27]
	v_pk_mul_f32 v[26:27], v[24:25], v[24:25]
	v_cvt_pk_bf16_f32 v24, v28, v29
	v_add_co_u32_e32 v28, vcc, s16, v138
	v_pk_mul_f32 v[30:31], v[30:31], v[30:31]
	v_addc_co_u32_e32 v29, vcc, 0, v139, vcc
	v_cvt_pk_bf16_f32 v25, v30, v31
	v_max_f32_e32 v21, 0, v21
	v_max_f32_e32 v20, 0, v20
	v_max_f32_e32 v23, 0, v23
	v_max_f32_e32 v22, 0, v22
	v_max_f32_e32 v17, 0, v17
	v_max_f32_e32 v16, 0, v16
	v_max_f32_e32 v19, 0, v19
	v_max_f32_e32 v18, 0, v18
	v_cvt_pk_bf16_f32 v26, v26, v27
	v_cvt_pk_bf16_f32 v27, v34, v35
	global_store_dwordx4 v[28:29], v[24:27], off nt
	v_pk_mul_f32 v[22:23], v[22:23], v[22:23]
	v_pk_mul_f32 v[20:21], v[20:21], v[20:21]
	v_pk_mul_f32 v[24:25], v[18:19], v[18:19]
	v_pk_mul_f32 v[18:19], v[16:17], v[16:17]
	v_cvt_pk_bf16_f32 v16, v20, v21
	v_cvt_pk_bf16_f32 v17, v22, v23
	s_mov_b64 s[16:17], 0x160000
	v_max_f32_e32 v13, 0, v13
	v_max_f32_e32 v12, 0, v12
	v_cvt_pk_bf16_f32 v18, v18, v19
	v_cvt_pk_bf16_f32 v19, v24, v25
	global_store_dwordx4 v[32:33], v[16:19], off offset:256 nt
	s_nop 1
	v_lshl_add_u64 v[16:17], v[138:139], 0, s[16:17]
	v_max_f32_e32 v9, 0, v9
	v_max_f32_e32 v8, 0, v8
	v_max_f32_e32 v11, 0, v11
	v_max_f32_e32 v10, 0, v10
	v_pk_mul_f32 v[12:13], v[12:13], v[12:13]
	s_mov_b32 s16, 0x160000
	v_max_f32_e32 v15, 0, v15
	v_max_f32_e32 v14, 0, v14
	v_pk_mul_f32 v[18:19], v[10:11], v[10:11]
	v_pk_mul_f32 v[10:11], v[8:9], v[8:9]
	v_cvt_pk_bf16_f32 v8, v12, v13
	v_add_co_u32_e32 v12, vcc, s16, v138
	v_pk_mul_f32 v[14:15], v[14:15], v[14:15]
	v_addc_co_u32_e32 v13, vcc, 0, v139, vcc
	v_cvt_pk_bf16_f32 v9, v14, v15
	v_max_f32_e32 v1, 0, v1
	v_max_f32_e32 v0, 0, v0
	v_max_f32_e32 v3, 0, v3
	v_max_f32_e32 v2, 0, v2
	v_cvt_pk_bf16_f32 v10, v10, v11
	v_cvt_pk_bf16_f32 v11, v18, v19
	global_store_dwordx4 v[12:13], v[8:11], off nt
	v_max_f32_e32 v5, 0, v5
	v_max_f32_e32 v4, 0, v4
	v_max_f32_e32 v7, 0, v7
	v_max_f32_e32 v6, 0, v6
	v_pk_mul_f32 v[8:9], v[2:3], v[2:3]
	v_pk_mul_f32 v[2:3], v[0:1], v[0:1]
	s_andn2_b64 vcc, exec, s[2:3]
	s_mov_b64 s[2:3], -1
	v_pk_mul_f32 v[6:7], v[6:7], v[6:7]
	v_pk_mul_f32 v[4:5], v[4:5], v[4:5]
	s_nop 0
	v_cvt_pk_bf16_f32 v0, v4, v5
	v_cvt_pk_bf16_f32 v1, v6, v7
	v_cvt_pk_bf16_f32 v2, v2, v3
	v_cvt_pk_bf16_f32 v3, v8, v9
	global_store_dwordx4 v[16:17], v[0:3], off offset:256 nt
	s_cbranch_vccnz .LBB0_1238
	s_andn2_b64 vcc, exec, s[0:1]
	s_cbranch_vccnz .LBB0_1237
	s_barrier
	s_branch .LBB0_1237
